# rot preload + conv taps in LDS + double-buffered conv transpose tile (one barrier per item)
# speedup vs baseline: 1.0114x; 1.0063x over previous
.LBB0_944:
	s_lshl_b32 s14, s34, 1
	ds_read_b128 v[26:29], v72
	ds_read_b128 v[30:33], v73
	s_add_u32 s0, s0, s14
	s_addc_u32 s1, s1, 0
	v_lshl_add_u64 v[4:5], s[0:1], 0, v[0:1]
	v_mov_b32_e32 v65, v1
	v_mov_b32_e32 v67, v1
	v_lshl_add_u64 v[38:39], v[4:5], 0, v[64:65]
	v_lshl_add_u64 v[4:5], v[4:5], 0, v[66:67]
	s_waitcnt lgkmcnt(1)
	global_store_dwordx4 v[38:39], v[26:29], off
	s_waitcnt lgkmcnt(0)
	global_store_dwordx4 v[4:5], v[30:33], off
	v_xor_b32_e32 v71, 0x18000, v71
	v_xor_b32_e32 v72, 0x18000, v72
	v_xor_b32_e32 v73, 0x18000, v73
